# k11 + stick-breaking clamp fused (bit-identical) + 4-workgroup same-XCD group barriers replacing 9 row-block-local grid barriers (runtime XCC consistency check, falls back to grid barrier)
# speedup vs baseline: 1.1671x; 1.0202x over previous
; #define LAS __attribute__((address_space(3)))
; __device__ __forceinline__ unsigned xb_add(unsigned* p, unsigned v) { return __hip_atomic_fetch_add(p, v, __ATOMIC_RELAXED, __HIP_MEMORY_SCOPE_AGENT); }
; __device__ __forceinline__ unsigned xb_xcc_id() { return (unsigned)__builtin_amdgcn_s_getreg((3 << 11) | 20) & 0xFu; }
; __device__ __forceinline__ XcdBarrier xcd_barrier_post(unsigned* bar, volatile LAS unsigned* st) {
;     XcdBarrier b; b.bar = bar; b.x = xb_xcc_id(); b.st = st;
;     if (threadIdx.x == 0) (void)xb_add(&bar[XB_XCNT(b.x)], 1u);
;     return b;
; }
.LBB0_2:
	s_or_b64 exec, exec, s[0:1]
	s_waitcnt lgkmcnt(0)
	s_barrier
	s_add_u32 s0, s20, 0x3766100
	s_getreg_b32 s2, hwreg(HW_REG_XCC_ID, 0, 4)
	s_addc_u32 s1, s21, 0
	s_and_b32 s10, s2, 15
	s_mov_b64 s[2:3], exec
	v_readlane_b32 s6, v253, 4
	v_readlane_b32 s7, v253, 5
	s_and_b64 s[6:7], s[2:3], s[6:7]
	s_mov_b64 exec, s[6:7]
	s_cbranch_execz .LBB0_5
	s_mov_b64 s[6:7], exec
	v_mbcnt_lo_u32_b32 v1, s6, 0
	v_mbcnt_hi_u32_b32 v1, s7, v1
	v_cmp_eq_u32_e32 vcc, 0, v1
	s_and_b64 s[8:9], exec, vcc
	s_mov_b64 exec, s[8:9]
	s_cbranch_execz .LBB0_5
	s_lshl_b32 s8, s10, 8
	s_bcnt1_i32_b64 s6, s[6:7]
	v_mov_b32_e32 v1, s8
	v_mov_b32_e32 v2, s6
	global_atomic_add v1, v2, s[0:1] offset:1024
	s_and_b32 s8, s19, 7
	s_lshl_b32 s8, s8, 2
	s_lshl_b32 s9, 1, s10
	s_nop 1
	v_mov_b32_e32 v1, s8
	v_mov_b32_e32 v3, s9
	global_atomic_or v1, v3, s[0:1] offset:4

; #define LAS __attribute__((address_space(3)))
; #define MFMA32(a, b, c) __builtin_amdgcn_mfma_f32_32x32x16_bf16((a), (b), (c), 0, 0, 0)
; template <bool DIAG>
; __device__ __forceinline__ void stick_subtile(const bf16x8 (&k)[4], const bf16x8 (&v)[2][2], const bf16x8 (&q)[4], f32x16 (&o)[2], float& run, int r, int h) {
;     f32x16 z;
; #pragma unroll
;     for (int i = 0; i < 16; ++i) z[i] = 0.f;
; #pragma unroll
;     for (int s = 0; s < 4; ++s) z = MFMA32(k[s], q[s], z);
; template <int TYPE>
; __device__ __forceinline__ void attn_unit(const bf16_t* QK, const bf16_t* VT, bf16_t* O, int bh, int qb, float lam, const float* normg, float outscale, int tid, LAS unsigned char* lds) {
;     ...
;         LAS const unsigned char* L = lds + (it & 1) * AT_BUF;
;         bf16x8 kf[2][4], vf[2][2][2];
; #pragma unroll
;         for (int st = 0; st < 2; ++st) {
; #pragma unroll
;             for (int s4 = 0; s4 < 4; ++s4) kf[st][s4] = ldsf(L + fk + st * 32 * AT_ROW + 32 * s4);
; #pragma unroll
;             for (int mt = 0; mt < 2; ++mt)
; #pragma unroll
;                 for (int s2 = 0; s2 < 2; ++s2) vf[st][mt][s2] = ldsf(L + fv + st * 64 + mt * 32 * AT_ROW + 32 * s2);
;         }
; #pragma unroll
;         for (int ss = 0; ss < 2; ++ss) {
;             const int st = TYPE ? 1 - ss : ss, kt = 2 * tt + st;
;             const bf16x8 (&qa)[2] = *(const bf16x8 (*)[2])&q[0]; const bf16x8 (&qb2)[2] = *(const bf16x8 (*)[2])&q[2];
;             if (kt < qg) {
;                 if (TYPE == 0) diff_subtile<false>(kf[st], vf[st], qa, qb2, o1, o2, m1, m2, l1, l2, r, h);
;                 else stick_subtile<false>(kf[st], vf[st], q, o1, run, r, h);
;             } else if (kt == qg) {
;                 if (TYPE == 0) diff_subtile<true>(kf[st], vf[st], qa, qb2, o1, o2, m1, m2, l1, l2, r, h);
;                 else stick_subtile<true>(kf[st], vf[st], q, o1, run, r, h);
;             }
.LBB0_1241:
	s_and_b32 s37, 1, s97
	s_cselect_b32 s39, 0, 0x4800
	s_add_i32 s39, s39, 0
	v_add3_u32 v36, s39, v250, v210
	v_add3_u32 v37, s39, v251, v210
	ds_read_b128 v[100:103], v36
	ds_read_b128 v[96:99], v36 offset:32
	ds_read_b128 v[92:95], v36 offset:64
	ds_read_b128 v[88:91], v36 offset:96
	ds_read_b128 v[84:87], v37 offset:9216
	ds_read_b128 v[80:83], v37 offset:9248
	ds_read_b128 v[76:79], v37 offset:13824
	ds_read_b128 v[72:75], v37 offset:13856
	ds_read_b128 v[32:35], v36 offset:4608
	ds_read_b128 v[128:131], v36 offset:4640
	ds_read_b128 v[124:127], v36 offset:4672
	ds_read_b128 v[120:123], v36 offset:4704
	ds_read_b128 v[116:119], v37 offset:9280
	ds_read_b128 v[112:115], v37 offset:9312
	ds_read_b128 v[108:111], v37 offset:13888
	ds_read_b128 v[104:107], v37 offset:13920
	s_add_i32 s39, s48, s47
	s_add_i32 s42, s39, 0x7f
	v_cmp_ge_i32_e32 vcc, s42, v137
	s_and_saveexec_b64 s[42:43], vcc
	s_xor_b64 s[42:43], exec, s[42:43]
	s_cbranch_execz .LBB0_1245
	v_cmp_eq_u32_e32 vcc, s47, v243
	s_and_saveexec_b64 s[44:45], vcc
	s_cbranch_execz .LBB0_1244
	s_waitcnt lgkmcnt(7)
	v_mfma_f32_32x32x16_bf16 v[32:47], v[32:35], v[48:51], 0
	s_or_b64 vcc, s[64:65], s[62:63]
	s_or_b64 s[68:69], vcc, s[60:61]
	s_or_b64 s[70:71], s[68:69], s[58:59]
	s_or_b64 s[72:73], s[70:71], s[56:57]
	s_or_b64 s[74:75], s[72:73], s[54:55]
	s_or_b64 s[76:77], s[74:75], s[52:53]
	v_readlane_b32 s80, v255, 0
	s_waitcnt lgkmcnt(6)
	v_mfma_f32_32x32x16_bf16 v[32:47], v[128:131], v[52:55], v[32:47]
	s_or_b64 s[78:79], s[76:77], s[50:51]
	v_readlane_b32 s81, v255, 1
	v_readlane_b32 s82, v254, 62
	s_or_b64 s[80:81], s[78:79], s[80:81]
	v_readlane_b32 s83, v254, 63
	v_readlane_b32 s84, v254, 60
	s_or_b64 s[82:83], s[80:81], s[82:83]
	s_waitcnt lgkmcnt(5)
	v_mfma_f32_32x32x16_bf16 v[32:47], v[124:127], v[56:59], v[32:47]
	v_readlane_b32 s85, v254, 61
	v_readlane_b32 s86, v254, 58
	s_or_b64 s[84:85], s[82:83], s[84:85]
	v_readlane_b32 s87, v254, 59
	v_readlane_b32 s88, v254, 56
	s_or_b64 s[86:87], s[84:85], s[86:87]
	v_readlane_b32 s89, v254, 57
	s_waitcnt lgkmcnt(4)
; #define MFMA32(a, b, c) __builtin_amdgcn_mfma_f32_32x32x16_bf16((a), (b), (c), 0, 0, 0)
; __device__ __forceinline__ float xor32_get(float v, int h) { const unsigned u = __float_as_uint(v); auto r = __builtin_amdgcn_permlane32_swap(u, u, false, false); return __uint_as_float(h ? r[0] : r[1]); }
; template <bool DIAG>
; __device__ __forceinline__ void stick_subtile(const bf16x8 (&k)[4], const bf16x8 (&v)[2][2], const bf16x8 (&q)[4], f32x16 (&o)[2], float& run, int r, int h) {
;     ...
;     f32x16 be, sy;
; #pragma unroll
;     for (int i = 0; i < 16; ++i) { const float t = __expf(-fmaxf(z[i] * 0.125f, -80.f)); const float rc = __builtin_amdgcn_rcpf(1.f + t); be[i] = rc; sy[i] = t * rc; }
;     if (DIAG) {
; #pragma unroll
;         for (int i = 0; i < 16; ++i) { const int kk = 16 * (i >> 3) + 8 * h + (i & 7); if (kk >= r) { be[i] = 0.f; sy[i] = 1.f; } }
;     }
;     f32x16 suf; float tot[2];
; #pragma unroll
;     for (int gq = 0; gq < 2; ++gq) {
;         float acc = 1.f;
; #pragma unroll
;         for (int j = 7; j >= 0; --j) { suf[8 * gq + j] = acc; acc *= sy[8 * gq + j]; }
;         tot[gq] = acc;
;     }
;     const float pt0 = xor32_get(tot[0], h), pt1 = xor32_get(tot[1], h);
;     const float after0 = run * (h ? (pt1 * tot[1]) : (pt0 * tot[1] * pt1));
;     const float after1 = run * (h ? 1.f : pt1);
;     f32x16 w;
; #pragma unroll
;     for (int i = 0; i < 16; ++i) w[i] = be[i] * (i < 8 ? after0 : after1) * suf[i];
;     run *= (tot[0] * tot[1]) * (pt0 * pt1);
;     const bf16x8 p0 = pack8(w, 0), p1 = pack8(w, 1);
;     o[0] = MFMA32(v[0][0], p0, o[0]); o[0] = MFMA32(v[0][1], p1, o[0]);
;     o[1] = MFMA32(v[1][0], p0, o[1]); o[1] = MFMA32(v[1][1], p1, o[1]);
	v_mfma_f32_32x32x16_bf16 v[32:47], v[120:123], v[60:63], v[32:47]
	v_readlane_b32 s90, v254, 54
	s_or_b64 s[88:89], s[86:87], s[88:89]
	v_readlane_b32 s91, v254, 55
	v_readlane_b32 s92, v254, 52
	s_or_b64 s[90:91], s[88:89], s[90:91]
	v_readlane_b32 s93, v254, 53
	s_or_b64 s[92:93], s[90:91], s[92:93]
	s_nop 4
	v_mul_f32_e32 v32, 0xbe38aa3b, v32
	v_mul_f32_e32 v36, 0xbe38aa3b, v36
	v_mul_f32_e32 v37, 0xbe38aa3b, v37
	v_mul_f32_e32 v46, 0xbe38aa3b, v46
	v_mul_f32_e32 v47, 0xbe38aa3b, v47
	v_min_f32_e32 v32, 0x42e6d4ca, v32
	v_min_f32_e32 v36, 0x42e6d4ca, v36
	v_min_f32_e32 v37, 0x42e6d4ca, v37
	v_mul_f32_e32 v44, 0xbe38aa3b, v44
	v_mul_f32_e32 v45, 0xbe38aa3b, v45
	v_min_f32_e32 v46, 0x42e6d4ca, v46
	v_min_f32_e32 v47, 0x42e6d4ca, v47
	v_mul_f32_e32 v33, 0xbe38aa3b, v33
	v_min_f32_e32 v44, 0x42e6d4ca, v44
	v_min_f32_e32 v45, 0x42e6d4ca, v45
	v_min_f32_e32 v33, 0x42e6d4ca, v33
	v_exp_f32_e32 v32, v32
	v_exp_f32_e32 v36, v36
	v_exp_f32_e32 v37, v37
	v_mul_f32_e32 v42, 0xbe38aa3b, v42
	v_mul_f32_e32 v43, 0xbe38aa3b, v43
	v_exp_f32_e32 v46, v46
	v_exp_f32_e32 v47, v47
	v_mul_f32_e32 v34, 0xbe38aa3b, v34
	v_mul_f32_e32 v35, 0xbe38aa3b, v35
	v_min_f32_e32 v42, 0x42e6d4ca, v42
	v_min_f32_e32 v43, 0x42e6d4ca, v43
	v_exp_f32_e32 v44, v44
	v_exp_f32_e32 v45, v45
	v_mul_f32_e32 v38, 0xbe38aa3b, v38
	v_min_f32_e32 v34, 0x42e6d4ca, v34
	v_min_f32_e32 v35, 0x42e6d4ca, v35
	v_exp_f32_e32 v33, v33
	v_mul_f32_e32 v39, 0xbe38aa3b, v39
	v_mul_f32_e32 v40, 0xbe38aa3b, v40
	v_mul_f32_e32 v41, 0xbe38aa3b, v41
	v_min_f32_e32 v124, 0x42e6d4ca, v38
	v_min_f32_e32 v39, 0x42e6d4ca, v39
	v_min_f32_e32 v40, 0x42e6d4ca, v40
	v_min_f32_e32 v41, 0x42e6d4ca, v41
	v_exp_f32_e32 v42, v42
	v_exp_f32_e32 v43, v43
	v_exp_f32_e32 v34, v34
	v_exp_f32_e32 v35, v35
	v_add_f32_e32 v38, 1.0, v32
	v_add_f32_e32 v125, 1.0, v36
	v_add_f32_e32 v126, 1.0, v37
	v_add_f32_e32 v140, 1.0, v46
	v_add_f32_e32 v141, 1.0, v47
	v_rcp_f32_e32 v120, v38
	v_rcp_f32_e32 v38, v125
	v_exp_f32_e32 v124, v124
	v_exp_f32_e32 v125, v39
	v_rcp_f32_e32 v39, v126
	v_exp_f32_e32 v40, v40
	v_exp_f32_e32 v41, v41
	v_add_f32_e32 v138, 1.0, v44
	v_add_f32_e32 v139, 1.0, v45
	v_rcp_f32_e32 v140, v140
	v_rcp_f32_e32 v141, v141
	v_add_f32_e32 v121, 1.0, v33
	v_rcp_f32_e32 v138, v138
	v_rcp_f32_e32 v139, v139
	v_rcp_f32_e32 v121, v121
	v_add_f32_e32 v130, 1.0, v42
	v_add_f32_e32 v131, 1.0, v43
	v_add_f32_e32 v122, 1.0, v34
	v_add_f32_e32 v123, 1.0, v35
	v_rcp_f32_e32 v130, v130
	v_rcp_f32_e32 v131, v131
	v_rcp_f32_e32 v122, v122
	v_rcp_f32_e32 v123, v123
	v_add_f32_e32 v126, 1.0, v124
	v_add_f32_e32 v127, 1.0, v125
	v_add_f32_e32 v128, 1.0, v40
	v_add_f32_e32 v129, 1.0, v41
	v_pk_mul_f32 v[36:37], v[36:37], v[38:39]
	v_pk_mul_f32 v[46:47], v[46:47], v[140:141]
	v_rcp_f32_e32 v126, v126
	v_rcp_f32_e32 v127, v127
	v_rcp_f32_e32 v128, v128
	v_rcp_f32_e32 v129, v129
	v_pk_mul_f32 v[44:45], v[44:45], v[138:139]
	v_cndmask_b32_e32 v142, 1.0, v46, vcc
	v_cndmask_b32_e64 v151, 1.0, v36, s[86:87]
	v_cndmask_b32_e64 v36, 1.0, v47, s[64:65]
	v_pk_mul_f32 v[32:33], v[32:33], v[120:121]
	v_cndmask_b32_e64 v143, 1.0, v45, s[68:69]
	s_or_b64 s[94:95], s[92:93], s[4:5]
	v_cndmask_b32_e64 v47, 0, v121, s[92:93]
	v_mul_f32_e32 v121, v36, v142
	v_pk_mul_f32 v[42:43], v[42:43], v[130:131]
	v_cndmask_b32_e64 v144, 1.0, v44, s[70:71]
	v_cndmask_b32_e64 v46, 0, v120, s[94:95]
	v_mul_f32_e32 v120, v143, v121
	v_pk_mul_f32 v[34:35], v[34:35], v[122:123]
	v_cndmask_b32_e64 v145, 1.0, v43, s[72:73]
	v_cndmask_b32_e64 v45, 0, v123, s[88:89]
	v_mul_f32_e32 v123, v144, v120
	v_pk_mul_f32 v[124:125], v[124:125], v[126:127]
	v_pk_mul_f32 v[40:41], v[40:41], v[128:129]
	v_cndmask_b32_e64 v146, 1.0, v42, s[74:75]
	v_cndmask_b32_e64 v44, 0, v122, s[90:91]
	v_mul_f32_e32 v122, v145, v123
	v_cndmask_b32_e64 v147, 1.0, v41, s[76:77]
	v_cndmask_b32_e64 v148, 1.0, v40, s[78:79]
	v_cndmask_b32_e64 v40, 1.0, v125, s[80:81]
	v_mul_f32_e32 v125, v146, v122
	v_cndmask_b32_e64 v149, 1.0, v124, s[82:83]
	v_mul_f32_e32 v124, v147, v125
	v_cndmask_b32_e64 v41, 0, v127, s[80:81]
	v_mul_f32_e32 v127, v148, v124
	v_cndmask_b32_e64 v42, 0, v128, s[78:79]
	v_cndmask_b32_e64 v157, 0, v126, s[82:83]
	v_mov_b32_e32 v126, v127
	v_mov_b32_e32 v128, v127
	v_cndmask_b32_e64 v150, 1.0, v37, s[84:85]
	v_cndmask_b32_e64 v43, 0, v129, s[76:77]
	v_permlane32_swap_b32_e32 v126, v128
	v_mul_f32_e32 v129, v40, v149
	v_cndmask_b32_e64 v126, v126, v128, s[66:67]
	v_mul_f32_e32 v128, v150, v129
	v_cndmask_b32_e64 v152, 1.0, v35, s[88:89]
	v_cndmask_b32_e64 v35, 0, v131, s[72:73]
	v_mul_f32_e32 v131, v151, v128
	v_cndmask_b32_e64 v153, 1.0, v34, s[90:91]
	v_cndmask_b32_e64 v34, 0, v130, s[74:75]
	v_mul_f32_e32 v130, v152, v131
	v_cndmask_b32_e64 v154, 1.0, v33, s[92:93]
	v_cndmask_b32_e64 v33, 0, v139, s[68:69]
	v_mul_f32_e32 v139, v153, v130
	v_cndmask_b32_e64 v155, 1.0, v32, s[94:95]
	v_cndmask_b32_e64 v32, 0, v138, s[70:71]
	v_mul_f32_e32 v138, v154, v139
	v_cndmask_b32_e64 v37, 0, v141, s[64:65]
	v_mul_f32_e32 v141, v155, v138
	v_cndmask_b32_e32 v156, 0, v140, vcc
	v_mov_b32_e32 v140, v141
	v_mov_b32_e32 v142, v141
	s_nop 1
	v_permlane32_swap_b32_e32 v140, v142
	v_cndmask_b32_e64 v140, v140, v142, s[66:67]
	v_mul_f32_e32 v142, v127, v140
	v_cndmask_b32_e64 v142, v127, v142, s[66:67]
	v_mul_f32_e32 v142, v142, v126
	v_cndmask_b32_e64 v39, 0, v39, s[84:85]
	v_cndmask_b32_e64 v38, 0, v38, s[86:87]
	v_cndmask_b32_e64 v143, 1.0, v126, s[66:67]
	v_mul_f32_e32 v142, v136, v142
	v_pk_mul_f32 v[38:39], v[38:39], v[142:143] op_sel_hi:[1,0]
	v_pk_mul_f32 v[46:47], v[46:47], v[142:143] op_sel_hi:[1,0]
	v_pk_mul_f32 v[38:39], v[128:129], v[38:39]
	v_mul_f32_e32 v128, v157, v142
	v_mov_b32_e32 v129, v142
	v_pk_mul_f32 v[44:45], v[44:45], v[142:143] op_sel_hi:[1,0]
	v_pk_mul_f32 v[40:41], v[40:41], v[128:129]
	v_mul_f32_e32 v128, v136, v143
	v_pk_mul_f32 v[46:47], v[138:139], v[46:47]
	v_pk_mul_f32 v[44:45], v[130:131], v[44:45]
	v_pk_mul_f32 v[34:35], v[128:129], v[34:35] op_sel_hi:[0,1]
	v_pk_mul_f32 v[32:33], v[128:129], v[32:33] op_sel_hi:[0,1]
	v_pk_mul_f32 v[122:123], v[34:35], v[122:123]
	v_pk_mul_f32 v[120:121], v[32:33], v[120:121]
	v_cvt_pk_bf16_f32 v32, v46, v47
	v_cvt_pk_bf16_f32 v33, v44, v45
	v_cvt_pk_bf16_f32 v34, v38, v39
	v_cvt_pk_bf16_f32 v35, v40, v41
	v_pk_mul_f32 v[42:43], v[128:129], v[42:43] op_sel_hi:[0,1]
	v_mul_f32_e32 v38, v128, v156
	s_waitcnt lgkmcnt(3)
	v_mfma_f32_32x32x16_bf16 v[16:31], v[116:119], v[32:35], v[16:31]
	v_mov_b32_e32 v39, v128
	v_mul_f32_e64 v42, v42, v124
	v_mul_f32_e64 v43, v43, v125
	v_mul_f32_e64 v40, v36, v38
	v_mul_f32_e64 v41, v37, v39
	v_cvt_pk_bf16_f32 v36, v42, v43
	v_cvt_pk_bf16_f32 v37, v122, v123
	v_cvt_pk_bf16_f32 v38, v120, v121
	v_cvt_pk_bf16_f32 v39, v40, v41
	s_waitcnt lgkmcnt(1)
	v_mfma_f32_32x32x16_bf16 v[0:15], v[108:111], v[32:35], v[0:15]
	v_mul_f32_e64 v32, v140, v126
	v_mul_f32_e64 v33, v141, v127
	v_mul_f32_e32 v32, v32, v33
	v_mul_f32_e32 v136, v136, v32
	v_mfma_f32_32x32x16_bf16 v[16:31], v[112:115], v[36:39], v[16:31]
	s_waitcnt lgkmcnt(0)
	v_mfma_f32_32x32x16_bf16 v[0:15], v[104:107], v[36:39], v[0:15]

; #define MFMA32(a, b, c) __builtin_amdgcn_mfma_f32_32x32x16_bf16((a), (b), (c), 0, 0, 0)
; __device__ __forceinline__ float xor32_get(float v, int h) { const unsigned u = __float_as_uint(v); auto r = __builtin_amdgcn_permlane32_swap(u, u, false, false); return __uint_as_float(h ? r[0] : r[1]); }
; template <bool DIAG>
; __device__ __forceinline__ void stick_subtile(const bf16x8 (&k)[4], const bf16x8 (&v)[2][2], const bf16x8 (&q)[4], f32x16 (&o)[2], float& run, int r, int h) {
;     f32x16 z;
; #pragma unroll
;     for (int i = 0; i < 16; ++i) z[i] = 0.f;
; #pragma unroll
;     for (int s = 0; s < 4; ++s) z = MFMA32(k[s], q[s], z);
;     f32x16 be, sy;
; #pragma unroll
;     for (int i = 0; i < 16; ++i) { const float t = __expf(-fmaxf(z[i] * 0.125f, -80.f)); const float rc = __builtin_amdgcn_rcpf(1.f + t); be[i] = rc; sy[i] = t * rc; }
;     if (DIAG) {
; #pragma unroll
;         for (int i = 0; i < 16; ++i) { const int kk = 16 * (i >> 3) + 8 * h + (i & 7); if (kk >= r) { be[i] = 0.f; sy[i] = 1.f; } }
;     }
;     f32x16 suf; float tot[2];
; #pragma unroll
;     for (int gq = 0; gq < 2; ++gq) {
;         float acc = 1.f;
; #pragma unroll
;         for (int j = 7; j >= 0; --j) { suf[8 * gq + j] = acc; acc *= sy[8 * gq + j]; }
;         tot[gq] = acc;
;     }
;     const float pt0 = xor32_get(tot[0], h), pt1 = xor32_get(tot[1], h);
;     const float after0 = run * (h ? (pt1 * tot[1]) : (pt0 * tot[1] * pt1));
;     const float after1 = run * (h ? 1.f : pt1);
;     f32x16 w;
; #pragma unroll
;     for (int i = 0; i < 16; ++i) w[i] = be[i] * (i < 8 ? after0 : after1) * suf[i];
;     run *= (tot[0] * tot[1]) * (pt0 * pt1);
;     const bf16x8 p0 = pack8(w, 0), p1 = pack8(w, 1);
;     o[0] = MFMA32(v[0][0], p0, o[0]); o[0] = MFMA32(v[0][1], p1, o[0]);
;     o[1] = MFMA32(v[1][0], p0, o[1]); o[1] = MFMA32(v[1][1], p1, o[1]);
.LBB0_1245:
	s_andn2_saveexec_b64 s[42:43], s[42:43]
	s_cbranch_execz .LBB0_1247
	s_waitcnt lgkmcnt(7)
	v_mfma_f32_32x32x16_bf16 v[32:47], v[32:35], v[48:51], 0
	s_waitcnt lgkmcnt(6)
	v_mfma_f32_32x32x16_bf16 v[32:47], v[128:131], v[52:55], v[32:47]
	s_waitcnt lgkmcnt(5)
	v_mfma_f32_32x32x16_bf16 v[32:47], v[124:127], v[56:59], v[32:47]
	s_waitcnt lgkmcnt(4)
	v_mfma_f32_32x32x16_bf16 v[32:47], v[120:123], v[60:63], v[32:47]
	s_nop 11
	v_mul_f32_e32 v37, 0xbe38aa3b, v37
	v_mul_f32_e32 v33, 0xbe38aa3b, v33
	v_mul_f32_e32 v34, 0xbe38aa3b, v34
	v_mul_f32_e32 v36, 0xbe38aa3b, v36
	v_min_f32_e32 v37, 0x42e6d4ca, v37
	v_min_f32_e32 v33, 0x42e6d4ca, v33
	v_min_f32_e32 v34, 0x42e6d4ca, v34
	v_min_f32_e32 v36, 0x42e6d4ca, v36
	v_exp_f32_e32 v37, v37
	v_exp_f32_e32 v33, v33
	v_exp_f32_e32 v34, v34
	v_exp_f32_e32 v36, v36
	v_mul_f32_e32 v38, 0xbe38aa3b, v38
	v_min_f32_e32 v121, 0x42e6d4ca, v38
	v_mul_f32_e32 v39, 0xbe38aa3b, v39
	v_add_f32_e32 v125, 1.0, v37
	v_min_f32_e32 v39, 0x42e6d4ca, v39
	v_add_f32_e32 v120, 1.0, v33
	v_add_f32_e32 v122, 1.0, v34
	v_add_f32_e32 v124, 1.0, v36
	v_rcp_f32_e32 v163, v125
	v_exp_f32_e32 v125, v121
	v_rcp_f32_e32 v159, v120
	v_rcp_f32_e32 v120, v122
	v_rcp_f32_e32 v122, v124
	v_exp_f32_e32 v124, v39
	v_add_f32_e32 v39, 1.0, v125
	v_rcp_f32_e32 v127, v39
	v_mul_f32_e32 v46, 0xbe38aa3b, v46
	v_add_f32_e32 v39, 1.0, v124
	v_rcp_f32_e32 v126, v39
	v_mul_f32_e32 v39, 0xbe38aa3b, v40
	v_min_f32_e32 v39, 0x42e6d4ca, v39
	v_exp_f32_e32 v40, v39
	v_mul_f32_e32 v39, 0xbe38aa3b, v41
	v_min_f32_e32 v39, 0x42e6d4ca, v39
	v_exp_f32_e32 v39, v39
	v_add_f32_e32 v41, 1.0, v40
	v_rcp_f32_e32 v128, v41
	v_min_f32_e32 v46, 0x42e6d4ca, v46
	v_add_f32_e32 v41, 1.0, v39
	v_rcp_f32_e32 v164, v41
	v_mul_f32_e32 v41, 0xbe38aa3b, v42
	v_mul_f32_e32 v42, 0xbe38aa3b, v43
	v_min_f32_e32 v42, 0x42e6d4ca, v42
	v_min_f32_e32 v41, 0x42e6d4ca, v41
	v_exp_f32_e32 v43, v42
	v_exp_f32_e32 v42, v41
	v_add_f32_e32 v41, 1.0, v43
	v_rcp_f32_e32 v165, v41
	v_mul_f32_e32 v41, v39, v164
	v_add_f32_e32 v39, 1.0, v42
	v_rcp_f32_e32 v130, v39
	v_mul_f32_e32 v39, 0xbe38aa3b, v44
	v_mul_f32_e32 v44, 0xbe38aa3b, v45
	v_min_f32_e32 v44, 0x42e6d4ca, v44
	v_exp_f32_e32 v139, v46
	v_mul_f32_e32 v46, 0xbe38aa3b, v47
	v_exp_f32_e32 v45, v44
	v_min_f32_e32 v46, 0x42e6d4ca, v46
	v_mul_f32_e32 v35, 0xbe38aa3b, v35
	v_min_f32_e32 v39, 0x42e6d4ca, v39
	v_exp_f32_e32 v138, v46
	v_min_f32_e32 v35, 0x42e6d4ca, v35
	v_exp_f32_e32 v44, v39
	v_add_f32_e32 v39, 1.0, v45
	v_exp_f32_e32 v35, v35
	v_rcp_f32_e32 v166, v39
	v_add_f32_e32 v39, 1.0, v139
	v_mul_f32_e32 v32, 0xbe38aa3b, v32
	v_rcp_f32_e32 v47, v39
	v_add_f32_e32 v39, 1.0, v138
	v_min_f32_e32 v32, 0x42e6d4ca, v32
	v_rcp_f32_e32 v46, v39
	v_exp_f32_e32 v32, v32
	v_add_f32_e32 v123, 1.0, v35
	v_pk_mul_f32 v[124:125], v[124:125], v[126:127]
	v_add_f32_e32 v39, 1.0, v44
	v_rcp_f32_e32 v161, v123
	v_rcp_f32_e32 v140, v39
	v_pk_mul_f32 v[142:143], v[124:125], v[124:125] op_sel:[0,1] op_sel_hi:[1,0]
	v_mul_f32_e32 v37, v37, v163
	v_pk_mul_f32 v[138:139], v[138:139], v[46:47]
	v_mov_b32_e32 v123, v142
	v_pk_mul_f32 v[36:37], v[36:37], v[122:123]
	v_pk_mul_f32 v[150:151], v[138:139], v[138:139] op_sel:[0,1] op_sel_hi:[1,0]
	v_add_f32_e32 v38, 1.0, v32
	v_mul_f32_e32 v45, v45, v166
	v_pk_mul_f32 v[144:145], v[36:37], v[36:37] op_sel:[0,1] op_sel_hi:[1,0]
	v_mov_b32_e32 v141, v150
	v_rcp_f32_e32 v38, v38
	v_mul_f32_e32 v35, v35, v161
	v_mov_b32_e32 v121, v144
	v_pk_mul_f32 v[44:45], v[44:45], v[140:141]
	v_pk_mul_f32 v[34:35], v[34:35], v[120:121]
	v_pk_mul_f32 v[152:153], v[44:45], v[44:45] op_sel:[0,1] op_sel_hi:[1,0]
	v_mul_f32_e32 v43, v43, v165
	v_pk_mul_f32 v[146:147], v[34:35], v[34:35] op_sel:[0,1] op_sel_hi:[1,0]
	v_mov_b32_e32 v131, v152
	v_mul_f32_e32 v33, v33, v159
	v_mov_b32_e32 v39, v146
	v_pk_mul_f32 v[42:43], v[42:43], v[130:131]
	v_pk_mul_f32 v[32:33], v[32:33], v[38:39]
	v_pk_mul_f32 v[154:155], v[42:43], v[42:43] op_sel:[0,1] op_sel_hi:[1,0]
	v_pk_mul_f32 v[148:149], v[32:33], v[32:33] op_sel:[0,1] op_sel_hi:[1,0]
	v_mov_b32_e32 v129, v154
	v_pk_mul_f32 v[40:41], v[40:41], v[128:129]
	v_mov_b32_e32 v39, v148
	v_mov_b32_e32 v121, v148
	v_pk_mul_f32 v[156:157], v[40:41], v[40:41] op_sel:[0,1] op_sel_hi:[1,0]
	s_nop 0
	v_permlane32_swap_b32_e32 v39, v121
	v_cndmask_b32_e64 v158, v39, v121, s[66:67]
	v_mov_b32_e32 v39, v156
	v_mov_b32_e32 v121, v156
	s_nop 1
	v_permlane32_swap_b32_e32 v39, v121
	v_cndmask_b32_e64 v160, v39, v121, s[66:67]
	v_mul_f32_e32 v39, v156, v158
	v_cndmask_b32_e64 v39, v156, v39, s[66:67]
	v_mul_f32_e32 v39, v39, v160
	v_mul_f32_e32 v162, v136, v39
	v_mov_b32_e32 v39, v159
	v_pk_mul_f32 v[38:39], v[38:39], v[162:163] op_sel_hi:[1,0]
	v_pk_mov_b32 v[32:33], v[32:33], v[146:147] op_sel:[1,0]
	v_mov_b32_e32 v121, v161
	v_pk_mul_f32 v[32:33], v[32:33], v[38:39]
	v_pk_mul_f32 v[38:39], v[120:121], v[162:163] op_sel_hi:[1,0]
	v_pk_mov_b32 v[34:35], v[34:35], v[144:145] op_sel:[1,0]
	v_mov_b32_e32 v123, v163
	v_pk_mul_f32 v[34:35], v[34:35], v[38:39]
	v_pk_mul_f32 v[38:39], v[122:123], v[162:163] op_sel_hi:[1,0]
	v_pk_mov_b32 v[36:37], v[36:37], v[142:143] op_sel:[1,0]
	v_mov_b32_e32 v125, v126
	v_pk_mul_f32 v[36:37], v[36:37], v[38:39]
	v_mul_f32_e32 v38, v127, v162
	v_mov_b32_e32 v39, v162
	v_pk_mul_f32 v[38:39], v[124:125], v[38:39]
	v_cvt_pk_bf16_f32 v32, v32, v33
	v_cvt_pk_bf16_f32 v33, v34, v35
	v_cvt_pk_bf16_f32 v34, v36, v37
	v_cvt_pk_bf16_f32 v35, v38, v39
	v_cndmask_b32_e64 v129, 1.0, v160, s[66:67]
	v_mul_f32_e32 v120, v136, v129
	s_waitcnt lgkmcnt(3)
	v_mfma_f32_32x32x16_bf16 v[16:31], v[116:119], v[32:35], v[16:31]
	v_mov_b32_e32 v129, v164
	v_mul_f32_e64 v122, v128, v120
	v_mul_f32_e64 v123, v129, v120
	v_pk_mov_b32 v[40:41], v[40:41], v[154:155] op_sel:[1,0]
	v_mov_b32_e32 v131, v165
	v_pk_mul_f32 v[40:41], v[122:123], v[40:41]
	v_pk_mul_f32 v[122:123], v[130:131], v[120:121] op_sel_hi:[1,0]
	v_pk_mov_b32 v[42:43], v[42:43], v[152:153] op_sel:[1,0]
	s_waitcnt lgkmcnt(1)
	v_mfma_f32_32x32x16_bf16 v[0:15], v[108:111], v[32:35], v[0:15]
	v_mov_b32_e32 v141, v166
	v_mul_f32_e64 v42, v122, v42
	v_mul_f32_e64 v43, v123, v43
	v_mul_f32_e64 v122, v140, v120
	v_mul_f32_e64 v123, v141, v120
	v_pk_mov_b32 v[44:45], v[44:45], v[150:151] op_sel:[1,0]
	v_mov_b32_e32 v139, v46
	v_pk_mul_f32 v[44:45], v[122:123], v[44:45]
	v_mul_f32_e32 v122, v47, v120
	v_mov_b32_e32 v123, v120
	v_pk_mul_f32 v[46:47], v[138:139], v[122:123]
	v_cvt_pk_bf16_f32 v36, v40, v41
	v_cvt_pk_bf16_f32 v37, v42, v43
	v_cvt_pk_bf16_f32 v38, v44, v45
	v_cvt_pk_bf16_f32 v39, v46, v47
	v_mov_b32_e32 v159, v148
	v_mov_b32_e32 v161, v156
	v_mfma_f32_32x32x16_bf16 v[16:31], v[112:115], v[36:39], v[16:31]
	v_mul_f32_e64 v32, v158, v160
	v_mul_f32_e64 v33, v159, v161
	v_mul_f32_e32 v32, v32, v33
	v_mul_f32_e32 v136, v136, v32
	s_waitcnt lgkmcnt(0)
	v_mfma_f32_32x32x16_bf16 v[0:15], v[104:107], v[36:39], v[0:15]

; #define MFMA32(a, b, c) __builtin_amdgcn_mfma_f32_32x32x16_bf16((a), (b), (c), 0, 0, 0)
; template <bool DIAG>
; __device__ __forceinline__ void stick_subtile(const bf16x8 (&k)[4], const bf16x8 (&v)[2][2], const bf16x8 (&q)[4], f32x16 (&o)[2], float& run, int r, int h) {
;     ...
;     for (int s = 0; s < 4; ++s) z = MFMA32(k[s], q[s], z);
;     f32x16 be, sy;
; #pragma unroll
;     for (int i = 0; i < 16; ++i) { const float t = __expf(-fmaxf(z[i] * 0.125f, -80.f)); const float rc = __builtin_amdgcn_rcpf(1.f + t); be[i] = rc; sy[i] = t * rc; }
;     if (DIAG) {
; #pragma unroll
;         for (int i = 0; i < 16; ++i) { const int kk = 16 * (i >> 3) + 8 * h + (i & 7); if (kk >= r) { be[i] = 0.f; sy[i] = 1.f; } }
.LBB0_1250:
	v_cmp_eq_u32_e32 vcc, s47, v211
	s_and_saveexec_b64 s[44:45], vcc
	s_cbranch_execz .LBB0_1252
	s_waitcnt lgkmcnt(7)
	v_mfma_f32_32x32x16_bf16 v[32:47], v[100:103], v[48:51], 0
	s_or_b64 vcc, s[64:65], s[62:63]
	s_or_b64 s[68:69], vcc, s[60:61]
	s_or_b64 s[70:71], s[68:69], s[58:59]
	s_or_b64 s[72:73], s[70:71], s[56:57]
	s_or_b64 s[74:75], s[72:73], s[54:55]
	s_or_b64 s[76:77], s[74:75], s[52:53]
	v_readlane_b32 s80, v255, 0
	v_mfma_f32_32x32x16_bf16 v[32:47], v[96:99], v[52:55], v[32:47]
	s_or_b64 s[78:79], s[76:77], s[50:51]
	v_readlane_b32 s81, v255, 1
	v_readlane_b32 s82, v254, 62
	s_or_b64 s[80:81], s[78:79], s[80:81]
	v_readlane_b32 s83, v254, 63
	v_readlane_b32 s84, v254, 60
	s_or_b64 s[82:83], s[80:81], s[82:83]
	v_mfma_f32_32x32x16_bf16 v[32:47], v[92:95], v[56:59], v[32:47]
	v_readlane_b32 s85, v254, 61
	v_readlane_b32 s86, v254, 58
	s_or_b64 s[84:85], s[82:83], s[84:85]
	v_readlane_b32 s87, v254, 59
	v_readlane_b32 s88, v254, 56
	s_or_b64 s[86:87], s[84:85], s[86:87]
	v_readlane_b32 s89, v254, 57
	v_mfma_f32_32x32x16_bf16 v[32:47], v[88:91], v[60:63], v[32:47]
	v_readlane_b32 s90, v254, 54
	s_or_b64 s[88:89], s[86:87], s[88:89]
	v_readlane_b32 s91, v254, 55
	v_readlane_b32 s92, v254, 52
	s_or_b64 s[90:91], s[88:89], s[90:91]
	v_readlane_b32 s93, v254, 53
	s_or_b64 s[92:93], s[90:91], s[92:93]
	s_nop 4
	v_mul_f32_e32 v32, 0xbe38aa3b, v32
	v_mul_f32_e32 v36, 0xbe38aa3b, v36
	v_mul_f32_e32 v37, 0xbe38aa3b, v37
	v_mul_f32_e32 v46, 0xbe38aa3b, v46
	v_mul_f32_e32 v47, 0xbe38aa3b, v47
	v_min_f32_e32 v32, 0x42e6d4ca, v32
	v_min_f32_e32 v36, 0x42e6d4ca, v36
	v_min_f32_e32 v37, 0x42e6d4ca, v37
	v_mul_f32_e32 v44, 0xbe38aa3b, v44
	v_mul_f32_e32 v45, 0xbe38aa3b, v45
	v_min_f32_e32 v46, 0x42e6d4ca, v46
	v_min_f32_e32 v47, 0x42e6d4ca, v47
	v_mul_f32_e32 v33, 0xbe38aa3b, v33
	v_min_f32_e32 v44, 0x42e6d4ca, v44
	v_min_f32_e32 v45, 0x42e6d4ca, v45
	v_min_f32_e32 v33, 0x42e6d4ca, v33
	v_exp_f32_e32 v32, v32
	v_exp_f32_e32 v36, v36
	v_exp_f32_e32 v37, v37
	v_mul_f32_e32 v42, 0xbe38aa3b, v42
	v_mul_f32_e32 v43, 0xbe38aa3b, v43
	v_exp_f32_e32 v46, v46
	v_exp_f32_e32 v47, v47
	v_mul_f32_e32 v34, 0xbe38aa3b, v34
	v_mul_f32_e32 v35, 0xbe38aa3b, v35
	v_min_f32_e32 v42, 0x42e6d4ca, v42
	v_min_f32_e32 v43, 0x42e6d4ca, v43
	v_exp_f32_e32 v44, v44
	v_exp_f32_e32 v45, v45
	v_mul_f32_e32 v38, 0xbe38aa3b, v38
	v_min_f32_e32 v34, 0x42e6d4ca, v34
	v_min_f32_e32 v35, 0x42e6d4ca, v35
	v_exp_f32_e32 v33, v33
	v_mul_f32_e32 v39, 0xbe38aa3b, v39
	v_mul_f32_e32 v40, 0xbe38aa3b, v40
	v_mul_f32_e32 v41, 0xbe38aa3b, v41
	v_min_f32_e32 v92, 0x42e6d4ca, v38
	v_min_f32_e32 v39, 0x42e6d4ca, v39
	v_min_f32_e32 v40, 0x42e6d4ca, v40
	v_min_f32_e32 v41, 0x42e6d4ca, v41
	v_exp_f32_e32 v42, v42
	v_exp_f32_e32 v43, v43
	v_exp_f32_e32 v34, v34
	v_exp_f32_e32 v35, v35
	v_add_f32_e32 v38, 1.0, v32
	v_add_f32_e32 v93, 1.0, v36
	v_add_f32_e32 v94, 1.0, v37
	v_add_f32_e32 v102, 1.0, v46
	v_add_f32_e32 v103, 1.0, v47
	v_rcp_f32_e32 v88, v38
	v_rcp_f32_e32 v38, v93
	v_exp_f32_e32 v92, v92
	v_exp_f32_e32 v93, v39
	v_rcp_f32_e32 v39, v94
	v_exp_f32_e32 v40, v40
	v_exp_f32_e32 v41, v41
	v_add_f32_e32 v100, 1.0, v44
	v_add_f32_e32 v101, 1.0, v45
	v_rcp_f32_e32 v102, v102
	v_rcp_f32_e32 v103, v103
	v_add_f32_e32 v89, 1.0, v33
	v_rcp_f32_e32 v100, v100
	v_rcp_f32_e32 v101, v101
	v_rcp_f32_e32 v89, v89
	v_add_f32_e32 v98, 1.0, v42
	v_add_f32_e32 v99, 1.0, v43
	v_add_f32_e32 v90, 1.0, v34
	v_add_f32_e32 v91, 1.0, v35
	v_rcp_f32_e32 v98, v98
	v_rcp_f32_e32 v99, v99
	v_rcp_f32_e32 v90, v90
	v_rcp_f32_e32 v91, v91
	v_add_f32_e32 v94, 1.0, v92
	v_add_f32_e32 v95, 1.0, v93
	v_add_f32_e32 v96, 1.0, v40
	v_add_f32_e32 v97, 1.0, v41
	v_pk_mul_f32 v[36:37], v[36:37], v[38:39]
	v_pk_mul_f32 v[46:47], v[46:47], v[102:103]
	v_rcp_f32_e32 v94, v94
	v_rcp_f32_e32 v95, v95
	v_rcp_f32_e32 v96, v96
	v_rcp_f32_e32 v97, v97
	v_pk_mul_f32 v[44:45], v[44:45], v[100:101]
	s_waitcnt lgkmcnt(0)
; #define MFMA32(a, b, c) __builtin_amdgcn_mfma_f32_32x32x16_bf16((a), (b), (c), 0, 0, 0)
; __device__ __forceinline__ float xor32_get(float v, int h) { const unsigned u = __float_as_uint(v); auto r = __builtin_amdgcn_permlane32_swap(u, u, false, false); return __uint_as_float(h ? r[0] : r[1]); }
; template <bool DIAG>
; __device__ __forceinline__ void stick_subtile(const bf16x8 (&k)[4], const bf16x8 (&v)[2][2], const bf16x8 (&q)[4], f32x16 (&o)[2], float& run, int r, int h) {
;     ...
;     if (DIAG) {
; #pragma unroll
;         for (int i = 0; i < 16; ++i) { const int kk = 16 * (i >> 3) + 8 * h + (i & 7); if (kk >= r) { be[i] = 0.f; sy[i] = 1.f; } }
;     }
;     f32x16 suf; float tot[2];
; #pragma unroll
;     for (int gq = 0; gq < 2; ++gq) {
;         float acc = 1.f;
; #pragma unroll
;         for (int j = 7; j >= 0; --j) { suf[8 * gq + j] = acc; acc *= sy[8 * gq + j]; }
;         tot[gq] = acc;
;     }
;     const float pt0 = xor32_get(tot[0], h), pt1 = xor32_get(tot[1], h);
;     const float after0 = run * (h ? (pt1 * tot[1]) : (pt0 * tot[1] * pt1));
;     const float after1 = run * (h ? 1.f : pt1);
;     f32x16 w;
; #pragma unroll
;     for (int i = 0; i < 16; ++i) w[i] = be[i] * (i < 8 ? after0 : after1) * suf[i];
;     run *= (tot[0] * tot[1]) * (pt0 * pt1);
;     const bf16x8 p0 = pack8(w, 0), p1 = pack8(w, 1);
;     o[0] = MFMA32(v[0][0], p0, o[0]); o[0] = MFMA32(v[0][1], p1, o[0]);
;     o[1] = MFMA32(v[1][0], p0, o[1]); o[1] = MFMA32(v[1][1], p1, o[1]);
	v_cndmask_b32_e32 v104, 1.0, v46, vcc
	v_cndmask_b32_e64 v113, 1.0, v36, s[86:87]
	v_cndmask_b32_e64 v36, 1.0, v47, s[64:65]
	v_pk_mul_f32 v[32:33], v[32:33], v[88:89]
	v_cndmask_b32_e64 v105, 1.0, v45, s[68:69]
	s_or_b64 s[94:95], s[92:93], s[4:5]
	v_cndmask_b32_e64 v47, 0, v89, s[92:93]
	v_mul_f32_e32 v89, v36, v104
	v_pk_mul_f32 v[42:43], v[42:43], v[98:99]
	v_cndmask_b32_e64 v106, 1.0, v44, s[70:71]
	v_cndmask_b32_e64 v46, 0, v88, s[94:95]
	v_mul_f32_e32 v88, v105, v89
	v_pk_mul_f32 v[34:35], v[34:35], v[90:91]
	v_cndmask_b32_e64 v107, 1.0, v43, s[72:73]
	v_cndmask_b32_e64 v45, 0, v91, s[88:89]
	v_mul_f32_e32 v91, v106, v88
	v_pk_mul_f32 v[92:93], v[92:93], v[94:95]
	v_pk_mul_f32 v[40:41], v[40:41], v[96:97]
	v_cndmask_b32_e64 v108, 1.0, v42, s[74:75]
	v_cndmask_b32_e64 v44, 0, v90, s[90:91]
	v_mul_f32_e32 v90, v107, v91
	v_cndmask_b32_e64 v109, 1.0, v41, s[76:77]
	v_cndmask_b32_e64 v110, 1.0, v40, s[78:79]
	v_cndmask_b32_e64 v40, 1.0, v93, s[80:81]
	v_mul_f32_e32 v93, v108, v90
	v_cndmask_b32_e64 v111, 1.0, v92, s[82:83]
	v_mul_f32_e32 v92, v109, v93
	v_cndmask_b32_e64 v41, 0, v95, s[80:81]
	v_mul_f32_e32 v95, v110, v92
	v_cndmask_b32_e64 v42, 0, v96, s[78:79]
	v_cndmask_b32_e64 v119, 0, v94, s[82:83]
	v_mov_b32_e32 v94, v95
	v_mov_b32_e32 v96, v95
	v_cndmask_b32_e64 v112, 1.0, v37, s[84:85]
	v_cndmask_b32_e64 v43, 0, v97, s[76:77]
	v_permlane32_swap_b32_e32 v94, v96
	v_mul_f32_e32 v97, v40, v111
	v_cndmask_b32_e64 v94, v94, v96, s[66:67]
	v_mul_f32_e32 v96, v112, v97
	v_cndmask_b32_e64 v114, 1.0, v35, s[88:89]
	v_cndmask_b32_e64 v35, 0, v99, s[72:73]
	v_mul_f32_e32 v99, v113, v96
	v_cndmask_b32_e64 v115, 1.0, v34, s[90:91]
	v_cndmask_b32_e64 v34, 0, v98, s[74:75]
	v_mul_f32_e32 v98, v114, v99
	v_cndmask_b32_e64 v116, 1.0, v33, s[92:93]
	v_cndmask_b32_e64 v33, 0, v101, s[68:69]
	v_mul_f32_e32 v101, v115, v98
	v_cndmask_b32_e64 v117, 1.0, v32, s[94:95]
	v_cndmask_b32_e64 v32, 0, v100, s[70:71]
	v_mul_f32_e32 v100, v116, v101
	v_cndmask_b32_e64 v37, 0, v103, s[64:65]
	v_mul_f32_e32 v103, v117, v100
	v_cndmask_b32_e32 v118, 0, v102, vcc
	v_mov_b32_e32 v102, v103
	v_mov_b32_e32 v104, v103
	s_nop 1
	v_permlane32_swap_b32_e32 v102, v104
	v_cndmask_b32_e64 v102, v102, v104, s[66:67]
	v_mul_f32_e32 v104, v95, v102
	v_cndmask_b32_e64 v104, v95, v104, s[66:67]
	v_mul_f32_e32 v104, v104, v94
	v_cndmask_b32_e64 v39, 0, v39, s[84:85]
	v_cndmask_b32_e64 v38, 0, v38, s[86:87]
	v_cndmask_b32_e64 v105, 1.0, v94, s[66:67]
	v_mul_f32_e32 v104, v136, v104
	v_pk_mul_f32 v[38:39], v[38:39], v[104:105] op_sel_hi:[1,0]
	v_pk_mul_f32 v[46:47], v[46:47], v[104:105] op_sel_hi:[1,0]
	v_pk_mul_f32 v[38:39], v[96:97], v[38:39]
	v_mul_f32_e32 v96, v119, v104
	v_mov_b32_e32 v97, v104
	v_pk_mul_f32 v[44:45], v[44:45], v[104:105] op_sel_hi:[1,0]
	v_pk_mul_f32 v[40:41], v[40:41], v[96:97]
	v_mul_f32_e32 v96, v136, v105
	v_pk_mul_f32 v[46:47], v[100:101], v[46:47]
	v_pk_mul_f32 v[44:45], v[98:99], v[44:45]
	v_pk_mul_f32 v[34:35], v[96:97], v[34:35] op_sel_hi:[0,1]
	v_pk_mul_f32 v[32:33], v[96:97], v[32:33] op_sel_hi:[0,1]
	v_pk_mul_f32 v[90:91], v[34:35], v[90:91]
	v_pk_mul_f32 v[88:89], v[32:33], v[88:89]
	v_cvt_pk_bf16_f32 v32, v46, v47
	v_cvt_pk_bf16_f32 v33, v44, v45
	v_cvt_pk_bf16_f32 v34, v38, v39
	v_cvt_pk_bf16_f32 v35, v40, v41
	v_pk_mul_f32 v[42:43], v[96:97], v[42:43] op_sel_hi:[0,1]
	v_mul_f32_e32 v38, v96, v118
	v_mfma_f32_32x32x16_bf16 v[16:31], v[84:87], v[32:35], v[16:31]
	v_mov_b32_e32 v39, v96
	v_mul_f32_e64 v42, v42, v92
	v_mul_f32_e64 v43, v43, v93
	v_mul_f32_e64 v40, v36, v38
	v_mul_f32_e64 v41, v37, v39
	v_cvt_pk_bf16_f32 v36, v42, v43
	v_cvt_pk_bf16_f32 v37, v90, v91
	v_cvt_pk_bf16_f32 v38, v88, v89
	v_cvt_pk_bf16_f32 v39, v40, v41
	v_mfma_f32_32x32x16_bf16 v[0:15], v[76:79], v[32:35], v[0:15]
	v_mul_f32_e64 v32, v102, v94
	v_mul_f32_e64 v33, v103, v95
	v_mul_f32_e32 v32, v32, v33
	v_mul_f32_e32 v136, v136, v32
	v_mfma_f32_32x32x16_bf16 v[16:31], v[80:83], v[36:39], v[16:31]
	v_mfma_f32_32x32x16_bf16 v[0:15], v[72:75], v[36:39], v[0:15]

; #define MFMA32(a, b, c) __builtin_amdgcn_mfma_f32_32x32x16_bf16((a), (b), (c), 0, 0, 0)
; __device__ __forceinline__ float xor32_get(float v, int h) { const unsigned u = __float_as_uint(v); auto r = __builtin_amdgcn_permlane32_swap(u, u, false, false); return __uint_as_float(h ? r[0] : r[1]); }
; template <bool DIAG>
; __device__ __forceinline__ void stick_subtile(const bf16x8 (&k)[4], const bf16x8 (&v)[2][2], const bf16x8 (&q)[4], f32x16 (&o)[2], float& run, int r, int h) {
;     f32x16 z;
; #pragma unroll
;     for (int i = 0; i < 16; ++i) z[i] = 0.f;
; #pragma unroll
;     for (int s = 0; s < 4; ++s) z = MFMA32(k[s], q[s], z);
;     f32x16 be, sy;
; #pragma unroll
;     for (int i = 0; i < 16; ++i) { const float t = __expf(-fmaxf(z[i] * 0.125f, -80.f)); const float rc = __builtin_amdgcn_rcpf(1.f + t); be[i] = rc; sy[i] = t * rc; }
;     if (DIAG) {
; #pragma unroll
;         for (int i = 0; i < 16; ++i) { const int kk = 16 * (i >> 3) + 8 * h + (i & 7); if (kk >= r) { be[i] = 0.f; sy[i] = 1.f; } }
;     }
;     f32x16 suf; float tot[2];
; #pragma unroll
;     for (int gq = 0; gq < 2; ++gq) {
;         float acc = 1.f;
; #pragma unroll
;         for (int j = 7; j >= 0; --j) { suf[8 * gq + j] = acc; acc *= sy[8 * gq + j]; }
;         tot[gq] = acc;
;     }
;     const float pt0 = xor32_get(tot[0], h), pt1 = xor32_get(tot[1], h);
;     const float after0 = run * (h ? (pt1 * tot[1]) : (pt0 * tot[1] * pt1));
;     const float after1 = run * (h ? 1.f : pt1);
;     f32x16 w;
; #pragma unroll
;     for (int i = 0; i < 16; ++i) w[i] = be[i] * (i < 8 ? after0 : after1) * suf[i];
;     run *= (tot[0] * tot[1]) * (pt0 * pt1);
;     const bf16x8 p0 = pack8(w, 0), p1 = pack8(w, 1);
;     o[0] = MFMA32(v[0][0], p0, o[0]); o[0] = MFMA32(v[0][1], p1, o[0]);
;     o[1] = MFMA32(v[1][0], p0, o[1]); o[1] = MFMA32(v[1][1], p1, o[1]);
.LBB0_1253:
	s_waitcnt lgkmcnt(7)
	v_mfma_f32_32x32x16_bf16 v[32:47], v[100:103], v[48:51], 0
	v_mfma_f32_32x32x16_bf16 v[32:47], v[96:99], v[52:55], v[32:47]
	v_mfma_f32_32x32x16_bf16 v[32:47], v[92:95], v[56:59], v[32:47]
	v_mfma_f32_32x32x16_bf16 v[32:47], v[88:91], v[60:63], v[32:47]
	s_nop 11
	v_mul_f32_e32 v37, 0xbe38aa3b, v37
	v_mul_f32_e32 v33, 0xbe38aa3b, v33
	v_mul_f32_e32 v34, 0xbe38aa3b, v34
	v_mul_f32_e32 v36, 0xbe38aa3b, v36
	v_min_f32_e32 v37, 0x42e6d4ca, v37
	v_min_f32_e32 v33, 0x42e6d4ca, v33
	v_min_f32_e32 v34, 0x42e6d4ca, v34
	v_min_f32_e32 v36, 0x42e6d4ca, v36
	v_exp_f32_e32 v37, v37
	v_exp_f32_e32 v33, v33
	v_exp_f32_e32 v34, v34
	v_exp_f32_e32 v36, v36
	v_mul_f32_e32 v38, 0xbe38aa3b, v38
	v_min_f32_e32 v89, 0x42e6d4ca, v38
	v_mul_f32_e32 v39, 0xbe38aa3b, v39
	v_add_f32_e32 v93, 1.0, v37
	v_min_f32_e32 v39, 0x42e6d4ca, v39
	v_add_f32_e32 v88, 1.0, v33
	v_add_f32_e32 v90, 1.0, v34
	v_add_f32_e32 v92, 1.0, v36
	s_waitcnt lgkmcnt(5)
	v_rcp_f32_e32 v125, v93
	v_exp_f32_e32 v93, v89
	s_waitcnt lgkmcnt(4)
	v_rcp_f32_e32 v121, v88
	v_rcp_f32_e32 v88, v90
	v_rcp_f32_e32 v90, v92
	v_exp_f32_e32 v92, v39
	v_add_f32_e32 v39, 1.0, v93
	v_rcp_f32_e32 v95, v39
	v_mul_f32_e32 v46, 0xbe38aa3b, v46
	v_add_f32_e32 v39, 1.0, v92
	v_rcp_f32_e32 v94, v39
	v_mul_f32_e32 v39, 0xbe38aa3b, v40
	v_min_f32_e32 v39, 0x42e6d4ca, v39
	v_exp_f32_e32 v40, v39
	v_mul_f32_e32 v39, 0xbe38aa3b, v41
	v_min_f32_e32 v39, 0x42e6d4ca, v39
	v_exp_f32_e32 v39, v39
	v_add_f32_e32 v41, 1.0, v40
	v_rcp_f32_e32 v96, v41
	v_min_f32_e32 v46, 0x42e6d4ca, v46
	v_add_f32_e32 v41, 1.0, v39
	v_rcp_f32_e32 v126, v41
	v_mul_f32_e32 v41, 0xbe38aa3b, v42
	v_mul_f32_e32 v42, 0xbe38aa3b, v43
	v_min_f32_e32 v42, 0x42e6d4ca, v42
	v_min_f32_e32 v41, 0x42e6d4ca, v41
	v_exp_f32_e32 v43, v42
	v_exp_f32_e32 v42, v41
	v_add_f32_e32 v41, 1.0, v43
	v_rcp_f32_e32 v127, v41
	v_mul_f32_e32 v41, v39, v126
	v_add_f32_e32 v39, 1.0, v42
	v_rcp_f32_e32 v98, v39
	v_mul_f32_e32 v39, 0xbe38aa3b, v44
	v_mul_f32_e32 v44, 0xbe38aa3b, v45
	v_min_f32_e32 v44, 0x42e6d4ca, v44
	v_exp_f32_e32 v101, v46
	v_mul_f32_e32 v46, 0xbe38aa3b, v47
	v_exp_f32_e32 v45, v44
	v_min_f32_e32 v46, 0x42e6d4ca, v46
	v_mul_f32_e32 v35, 0xbe38aa3b, v35
	v_min_f32_e32 v39, 0x42e6d4ca, v39
	v_exp_f32_e32 v100, v46
	v_min_f32_e32 v35, 0x42e6d4ca, v35
	v_exp_f32_e32 v44, v39
	v_add_f32_e32 v39, 1.0, v45
	v_exp_f32_e32 v35, v35
	v_rcp_f32_e32 v128, v39
	v_add_f32_e32 v39, 1.0, v101
	v_mul_f32_e32 v32, 0xbe38aa3b, v32
	v_rcp_f32_e32 v47, v39
	v_add_f32_e32 v39, 1.0, v100
	v_min_f32_e32 v32, 0x42e6d4ca, v32
	v_rcp_f32_e32 v46, v39
	v_exp_f32_e32 v32, v32
	v_add_f32_e32 v91, 1.0, v35
	v_pk_mul_f32 v[92:93], v[92:93], v[94:95]
	v_add_f32_e32 v39, 1.0, v44
	v_rcp_f32_e32 v123, v91
	v_rcp_f32_e32 v102, v39
	s_waitcnt lgkmcnt(0)
	v_pk_mul_f32 v[104:105], v[92:93], v[92:93] op_sel:[0,1] op_sel_hi:[1,0]
	v_mul_f32_e32 v37, v37, v125
	v_pk_mul_f32 v[100:101], v[100:101], v[46:47]
	v_mov_b32_e32 v91, v104
	v_pk_mul_f32 v[36:37], v[36:37], v[90:91]
	v_pk_mul_f32 v[112:113], v[100:101], v[100:101] op_sel:[0,1] op_sel_hi:[1,0]
	v_add_f32_e32 v38, 1.0, v32
	v_mul_f32_e32 v45, v45, v128
	v_pk_mul_f32 v[106:107], v[36:37], v[36:37] op_sel:[0,1] op_sel_hi:[1,0]
	v_mov_b32_e32 v103, v112
	v_rcp_f32_e32 v38, v38
	v_mul_f32_e32 v35, v35, v123
	v_mov_b32_e32 v89, v106
	v_pk_mul_f32 v[44:45], v[44:45], v[102:103]
	v_pk_mul_f32 v[34:35], v[34:35], v[88:89]
	v_pk_mul_f32 v[114:115], v[44:45], v[44:45] op_sel:[0,1] op_sel_hi:[1,0]
	v_mul_f32_e32 v43, v43, v127
	v_pk_mul_f32 v[108:109], v[34:35], v[34:35] op_sel:[0,1] op_sel_hi:[1,0]
	v_mov_b32_e32 v99, v114
	v_mul_f32_e32 v33, v33, v121
	v_mov_b32_e32 v39, v108
	v_pk_mul_f32 v[42:43], v[42:43], v[98:99]
	v_pk_mul_f32 v[32:33], v[32:33], v[38:39]
	v_pk_mul_f32 v[116:117], v[42:43], v[42:43] op_sel:[0,1] op_sel_hi:[1,0]
	v_pk_mul_f32 v[110:111], v[32:33], v[32:33] op_sel:[0,1] op_sel_hi:[1,0]
	v_mov_b32_e32 v97, v116
	v_pk_mul_f32 v[40:41], v[40:41], v[96:97]
	v_mov_b32_e32 v39, v110
	v_mov_b32_e32 v89, v110
	v_pk_mul_f32 v[118:119], v[40:41], v[40:41] op_sel:[0,1] op_sel_hi:[1,0]
	s_nop 0
	v_permlane32_swap_b32_e32 v39, v89
	v_cndmask_b32_e64 v120, v39, v89, s[66:67]
	v_mov_b32_e32 v39, v118
	v_mov_b32_e32 v89, v118
	s_nop 1
	v_permlane32_swap_b32_e32 v39, v89
	v_cndmask_b32_e64 v122, v39, v89, s[66:67]
	v_mul_f32_e32 v39, v118, v120
	v_cndmask_b32_e64 v39, v118, v39, s[66:67]
	v_mul_f32_e32 v39, v39, v122
	v_mul_f32_e32 v124, v136, v39
	v_mov_b32_e32 v39, v121
	v_pk_mul_f32 v[38:39], v[38:39], v[124:125] op_sel_hi:[1,0]
	v_pk_mov_b32 v[32:33], v[32:33], v[108:109] op_sel:[1,0]
	v_mov_b32_e32 v89, v123
	v_pk_mul_f32 v[32:33], v[32:33], v[38:39]
	v_pk_mul_f32 v[38:39], v[88:89], v[124:125] op_sel_hi:[1,0]
	v_pk_mov_b32 v[34:35], v[34:35], v[106:107] op_sel:[1,0]
	v_mov_b32_e32 v91, v125
	v_pk_mul_f32 v[34:35], v[34:35], v[38:39]
	v_pk_mul_f32 v[38:39], v[90:91], v[124:125] op_sel_hi:[1,0]
	v_pk_mov_b32 v[36:37], v[36:37], v[104:105] op_sel:[1,0]
	v_mov_b32_e32 v93, v94
	v_pk_mul_f32 v[36:37], v[36:37], v[38:39]
	v_mul_f32_e32 v38, v95, v124
	v_mov_b32_e32 v39, v124
	v_pk_mul_f32 v[38:39], v[92:93], v[38:39]
	v_cvt_pk_bf16_f32 v32, v32, v33
	v_cvt_pk_bf16_f32 v33, v34, v35
	v_cvt_pk_bf16_f32 v34, v36, v37
	v_cvt_pk_bf16_f32 v35, v38, v39
	v_cndmask_b32_e64 v97, 1.0, v122, s[66:67]
	v_mul_f32_e32 v88, v136, v97
	v_mfma_f32_32x32x16_bf16 v[16:31], v[84:87], v[32:35], v[16:31]
	v_mov_b32_e32 v97, v126
	v_mul_f32_e64 v90, v96, v88
	v_mul_f32_e64 v91, v97, v88
	v_pk_mov_b32 v[40:41], v[40:41], v[116:117] op_sel:[1,0]
	v_mov_b32_e32 v99, v127
	v_pk_mul_f32 v[40:41], v[90:91], v[40:41]
	v_pk_mul_f32 v[90:91], v[98:99], v[88:89] op_sel_hi:[1,0]
	v_pk_mov_b32 v[42:43], v[42:43], v[114:115] op_sel:[1,0]
	v_mfma_f32_32x32x16_bf16 v[0:15], v[76:79], v[32:35], v[0:15]
	v_mov_b32_e32 v103, v128
	v_mul_f32_e64 v42, v90, v42
	v_mul_f32_e64 v43, v91, v43
	v_mul_f32_e64 v90, v102, v88
	v_mul_f32_e64 v91, v103, v88
	v_pk_mov_b32 v[44:45], v[44:45], v[112:113] op_sel:[1,0]
	v_mov_b32_e32 v101, v46
	v_pk_mul_f32 v[44:45], v[90:91], v[44:45]
	v_mul_f32_e32 v90, v47, v88
	v_mov_b32_e32 v91, v88
	v_pk_mul_f32 v[46:47], v[100:101], v[90:91]
	v_cvt_pk_bf16_f32 v36, v40, v41
	v_cvt_pk_bf16_f32 v37, v42, v43
	v_cvt_pk_bf16_f32 v38, v44, v45
	v_cvt_pk_bf16_f32 v39, v46, v47
	v_mov_b32_e32 v121, v110
	v_mov_b32_e32 v123, v118
	v_mfma_f32_32x32x16_bf16 v[16:31], v[80:83], v[36:39], v[16:31]
	v_mul_f32_e64 v32, v120, v122
	v_mul_f32_e64 v33, v121, v123
	v_mul_f32_e32 v32, v32, v33
	v_mul_f32_e32 v136, v136, v32
	v_mfma_f32_32x32x16_bf16 v[0:15], v[72:75], v[36:39], v[0:15]
	s_or_b64 exec, exec, s[42:43]
	s_andn2_b64 vcc, exec, s[40:41]
	s_cbranch_vccnz .LBB0_1238

; __device__ __forceinline__ unsigned xb_ld(unsigned* p)              { return __hip_atomic_load(p, __ATOMIC_RELAXED, __HIP_MEMORY_SCOPE_AGENT); }
; __device__ __forceinline__ unsigned xb_add(unsigned* p, unsigned v) { return __hip_atomic_fetch_add(p, v, __ATOMIC_RELAXED, __HIP_MEMORY_SCOPE_AGENT); }
; #define XB_SPIN(cond, bar) do { unsigned _sp = 0; while (cond) { __builtin_amdgcn_s_sleep(1); \
;     if ((++_sp & 255u) == 0u) { if (xb_ld(&(bar)[XB_TMO])) break; if (_sp > XB_SPIN_CAP) { atomicAdd(&(bar)[XB_TMO], 1u); break; } } } } while (0)
; __device__ __forceinline__ void xcd_barrier(const XcdBarrier& b) {
;     asm volatile("s_waitcnt vmcnt(0)" ::: "memory");
;     __syncthreads();
;     if (threadIdx.x == 0) {
;         unsigned* bar = b.bar;
;         __builtin_amdgcn_s_waitcnt(0);
;         unsigned nloc = b.st[0], nx = b.st[1];
;         if (nloc == 0u) { xcd_barrier_complete(bar, b.x, nloc, nx); b.st[0] = nloc; b.st[1] = nx; }
;         const unsigned old = xb_add(&bar[XB_XSUB(b.x)], 1u);
;         const unsigned gen = old / nloc;
;         if (old + 1u == (gen + 1u) * nloc) {
;             __builtin_amdgcn_fence(__ATOMIC_RELEASE, "agent");
;             asm volatile("s_waitcnt vmcnt(0)" ::: "memory");
;             const unsigned og = xb_add(&bar[XB_TOP], 1u);
;             const unsigned tg = og / nx;
;             if (og + 1u == (tg + 1u) * nx) xb_add(&bar[XB_TOPGEN], 1u);
;             else XB_SPIN(xb_ld(&bar[XB_TOPGEN]) == tg, bar);
;             __builtin_amdgcn_fence(__ATOMIC_ACQUIRE, "agent");
;             xb_add(&bar[XB_XGEN(b.x)], 1u);
;             asm volatile("s_waitcnt vmcnt(0)" ::: "memory");
;         } else {
;             XB_SPIN(xb_ld(&bar[XB_XGEN(b.x)]) == gen, bar);
;             __builtin_amdgcn_fence(__ATOMIC_ACQUIRE, "agent");
;             asm volatile("s_waitcnt vmcnt(0)" ::: "memory");
;         }
;     }
;     __syncthreads();
; }
.LBB0_1655:
	v_readlane_b32 s4, v253, 0
	s_mov_b32 s5, 0x2819a06
	s_cmpk_lg_u32 s4, 0x100
	s_cbranch_scc1 .Lgb_normal
	s_bitcmp1_b32 s5, s22
	s_cbranch_scc0 .Lgb_normal
	v_readlane_b32 s6, v253, 6
	v_readlane_b32 s7, v253, 7
	v_readlane_b32 s8, v254, 18
	s_and_b32 s9, s8, 7
	s_lshl_b32 s9, s9, 2
	v_mov_b32_e32 v4, s9
	s_and_b32 s8, s8, 63
	s_lshl_b32 s8, s8, 5
	s_addk_i32 s8, 0x3400
	v_mov_b32_e32 v1, s8
	v_mov_b32_e32 v2, 1
	global_load_dword v0, v4, s[6:7] offset:-508 sc1
	s_waitcnt vmcnt(0)
	v_readfirstlane_b32 s9, v0
	s_cmp_eq_u32 s9, 0
	s_cbranch_scc1 .Lgb_normal
	s_add_i32 s10, s9, -1
	s_and_b32 s10, s10, s9
	s_cmp_lg_u32 s10, 0
	s_cbranch_scc1 .Lgb_normal
	global_atomic_add v3, v1, v2, s[6:7] sc0
	s_waitcnt vmcnt(0)
	v_readfirstlane_b32 s9, v3
	s_andn2_b32 s9, s9, 3
	s_add_i32 s9, s9, 4
	s_mov_b32 s11, 0
.Lgb_spin:
	global_load_dword v0, v1, s[6:7] sc1
	s_waitcnt vmcnt(0)
	v_readfirstlane_b32 s10, v0
	s_sub_i32 s10, s10, s9
	s_cmp_lt_i32 s10, 0
	s_cbranch_scc0 .Lgb_done
	s_add_i32 s11, s11, 1
	s_cmp_gt_u32 s11, 0x100000
	s_cbranch_scc1 .Lgb_done
	s_sleep 1
	s_branch .Lgb_spin
.Lgb_done:
	buffer_inv sc1
	s_waitcnt vmcnt(0)
	s_branch .Lgb_to20

; __global__ void __launch_bounds__(512, 2) mk_fwd(Args a) {
;     ...
;     for (int ph = a.ph_lo; ph < a.ph_hi; ++ph) {
;         if (ph == PH_PER_LAYER || ph == 2 * PH_PER_LAYER - 1) continue;
;         run_phase(ph, lds);
;         if (ph + 1 < a.ph_hi) xcd_barrier(xb);
.Lgb_to20:
	s_getpc_b64 s[98:99]
